# v109 + attention tile path: tail V reads up front with two waits, band compare moved into the mask block, scalar zero-reference flag for the path dispatch
# baseline (speedup 1.0000x reference)
; #define ATT_STAGE(t, buf) do { _Pragma("unroll") for (int i_ = 0; i_ < 2; ++i_) { \
;         glds16(Kt + (size_t)(t) * 131072, ksrc[i_], (unsigned)__builtin_amdgcn_readfirstlane(ldsb + KBUF + (buf) * 16384 + (w * 2 + i_) * 1024)); \
;         glds16(Vt + (size_t)(t) * 131072, vsrc[i_], (unsigned)__builtin_amdgcn_readfirstlane(ldsb + VBUF + (buf) * 16384 + (w * 2 + i_) * 1024)); } } while (0)
; __device__ __forceinline__ void attn_unit(ATT_LAS unsigned char* lds, const bf16_t* Qg, const bf16_t* Kg, const bf16_t* Vg, bf16_t* Og, int b, int head, int qb, float lam, const float* subg) {
;     int tid = threadIdx.x; asm volatile("" : "+v"(tid));
;     const int lane = tid & 63, r = lane & 31, h = lane >> 5;
;     const int w = __builtin_amdgcn_readfirstlane(tid >> 6);
;     const size_t rowbase = (size_t)b * SEQ; const int q0 = qb * 256, NT = (q0 + 256) >> 6;
;     const int wq = (w < 4) ? w : 11 - w;
;     const char* Kt = (const char*)(Kg + rowbase * PITCH + head * 128);
;     const char* Vt = (const char*)(Vg + rowbase * PITCH + head * 128);
;     unsigned ksrc[2], vsrc[2];
; #pragma unroll
;     for (int i = 0; i < 2; ++i) { const int ii = w * 2 + i;
;         { const int row = 4 * ii + (lane >> 4), pc = lane & 15; ksrc[i] = (unsigned)(row * 2048 + ((pc ^ (row & 15)) << 4)); }
;         { const int row = 8 * (ii >> 1) + ((lane >> 2) & 7), ch = 4 * (2 * (ii & 1) + (lane >> 5)) + ((lane & 3) ^ ((row >> 2) & 3)); vsrc[i] = (unsigned)(row * 2048 + ch * 16); } }
;     const unsigned ldsb = (unsigned)(uintptr_t)lds;
;     ...
;     ATT_STAGE(0, 0);
;     { const char* Qw = (const char*)(Qg + (rowbase + q0 + wq * 32) * PITCH + head * 128);
; #pragma unroll
;       for (int i = 0; i < 8; ++i) { const int row = 4 * i + (lane >> 4), pc = lane & 15;
;           glds16(Qw, (unsigned)(row * 2048 + ((pc ^ (row & 15)) << 4)), (unsigned)__builtin_amdgcn_readfirstlane(ldsb + QBUF + w * 8192 + i * 1024)); } }
.LBB0_285:
	s_mov_b32 s100, 0x42800000
	s_mov_b32 s101, 0
	v_mov_b32_e32 v0, v190
	s_xor_b64 s[88:89], s[2:3], -1
	v_readfirstlane_b32 s4, v0
	s_ashr_i32 s4, s4, 6
	s_and_b64 s[2:3], s[2:3], exec
	s_cselect_b32 s5, s1, s0
	s_lshl_b32 s3, s4, 3
	v_lshrrev_b32_e32 v5, 2, v0
	v_and_or_b32 v5, v5, 7, s3
	v_bfe_u32 v3, v0, 4, 2
	v_lshrrev_b32_e32 v6, 2, v5
	v_or_b32_e32 v4, s3, v3
	v_xor_b32_e32 v6, v6, v0
	v_bitop3_b32 v8, s3, v0, v3 bitop3:0x36
	v_bfe_u32 v195, v0, 5, 1
	v_lshlrev_b32_e32 v7, 11, v4
	v_lshlrev_b32_e32 v8, 4, v8
	v_lshlrev_b32_e32 v6, 4, v6
	s_lshl_b32 s77, s4, 11
	s_add_i32 s2, s5, 0x100
	v_lshlrev_b32_e32 v5, 11, v5
	v_and_or_b32 v198, v8, s97, v7
	v_lshlrev_b32_e32 v7, 6, v195
	v_and_b32_e32 v6, 48, v6
	s_add_i32 s6, 0, 0x8000
	s_or_b32 s50, s77, 0x400
	s_lshr_b32 s76, s2, 6
	s_sub_i32 s2, 11, s4
	v_or3_b32 v199, v6, v7, v5
	v_or_b32_e32 v5, 4, v4
	v_bitop3_b32 v4, v4, v0, 4 bitop3:0x36
	s_add_i32 s3, s77, 0
	s_add_i32 s7, s77, s6
	s_add_i32 s8, s50, 0
	s_add_i32 s6, s50, s6
	s_mov_b32 s9, m0
	s_mov_b32 m0, s3
	s_nop 0
	global_load_lds_dwordx4 v198, s[64:65]
	s_mov_b32 m0, s9
	v_lshlrev_b32_e32 v5, 11, v5
	v_lshlrev_b32_e32 v4, 4, v4
	s_cmp_lt_i32 s4, 4
	s_mov_b32 s3, m0
	s_mov_b32 m0, s7
	s_nop 0
	global_load_lds_dwordx4 v199, s[66:67]
	s_mov_b32 m0, s3
	v_and_or_b32 v200, v4, s97, v5
	s_mov_b32 s3, m0
	s_mov_b32 m0, s8
	s_nop 0
	global_load_lds_dwordx4 v200, s[64:65]
	s_mov_b32 m0, s3
	s_cselect_b32 s2, s4, s2
	v_or_b32_e32 v201, 0x80, v199
	s_mov_b32 s3, m0
	s_mov_b32 m0, s6
	s_nop 0
	global_load_lds_dwordx4 v201, s[66:67]
	s_mov_b32 m0, s3
	s_lshl_b32 s6, s2, 5
	s_or_b32 s3, s68, s5
	s_ashr_i32 s7, s6, 31
	s_add_u32 s2, s3, s6
	s_addc_u32 s3, s69, s7
	s_lshl_b64 s[90:91], s[2:3], 10
	s_lshl_b64 s[2:3], s[2:3], 11
	s_add_u32 s2, s48, s2
	v_xor_b32_e32 v5, v3, v0
	s_addc_u32 s3, s49, s3
	v_lshlrev_b32_e32 v4, 11, v3
	v_lshlrev_b32_e32 v5, 4, v5
	s_add_u32 s2, s2, s42
	v_and_or_b32 v4, v5, s97, v4
	v_or_b32_e32 v5, 4, v3
	v_bitop3_b32 v6, v3, v0, 4 bitop3:0x36
	s_addc_u32 s3, s3, 0
	s_lshl_b32 s7, s4, 13
	v_lshlrev_b32_e32 v5, 11, v5
	v_lshlrev_b32_e32 v6, 4, v6
	s_add_i32 s51, s7, s99
	s_mov_b32 s8, m0
	s_mov_b32 m0, s51
	s_nop 0
	global_load_lds_dwordx4 v4, s[2:3]
	s_mov_b32 m0, s8
	v_and_or_b32 v5, v6, s97, v5
	s_add_i32 s7, s7, 0
	s_add_i32 s8, s7, 0x11400
	s_mov_b32 s9, m0
	s_mov_b32 m0, s8
	s_nop 0
	global_load_lds_dwordx4 v5, s[2:3]
	s_mov_b32 m0, s9
	v_or_b32_e32 v5, 8, v3
	v_bitop3_b32 v6, v3, v0, 8 bitop3:0x36
	v_lshlrev_b32_e32 v5, 11, v5
	v_lshlrev_b32_e32 v6, 4, v6
	v_and_or_b32 v5, v6, s97, v5
	s_add_i32 s8, s7, 0x11800
	s_mov_b32 s9, m0
	s_mov_b32 m0, s8
	s_nop 0
	global_load_lds_dwordx4 v5, s[2:3]
	s_mov_b32 m0, s9
	v_or_b32_e32 v5, 12, v3
	v_bitop3_b32 v6, v3, v0, 12 bitop3:0x36
	v_lshlrev_b32_e32 v5, 11, v5
	v_lshlrev_b32_e32 v6, 4, v6
	v_and_or_b32 v5, v6, s97, v5
	s_add_i32 s8, s7, 0x11c00
	s_mov_b32 s9, m0
	s_mov_b32 m0, s8
	s_nop 0
	global_load_lds_dwordx4 v5, s[2:3]
	s_mov_b32 m0, s9
	v_or_b32_e32 v4, 0x8000, v4
	s_add_i32 s8, s7, 0x12000
	s_mov_b32 s9, m0
	s_mov_b32 m0, s8
	s_nop 0
	global_load_lds_dwordx4 v4, s[2:3]
	s_mov_b32 m0, s9
	v_or_b32_e32 v4, 20, v3
	v_bitop3_b32 v5, v3, v0, 20 bitop3:0x36
	v_lshlrev_b32_e32 v4, 11, v4
	v_lshlrev_b32_e32 v5, 4, v5
	v_and_or_b32 v4, v5, s97, v4
	s_add_i32 s8, s7, 0x12400
	s_mov_b32 s9, m0
	s_mov_b32 m0, s8
	s_nop 0
	global_load_lds_dwordx4 v4, s[2:3]
	s_mov_b32 m0, s9
	v_or_b32_e32 v4, 24, v3
	v_bitop3_b32 v5, v3, v0, 24 bitop3:0x36
	v_lshlrev_b32_e32 v4, 11, v4
	v_lshlrev_b32_e32 v5, 4, v5
	v_and_or_b32 v4, v5, s97, v4
	s_add_i32 s8, s7, 0x12800
	s_mov_b32 s9, m0
	s_mov_b32 m0, s8
	s_nop 0
	global_load_lds_dwordx4 v4, s[2:3]
	s_mov_b32 m0, s9
	v_or_b32_e32 v4, 28, v3
	v_bitop3_b32 v3, v3, v0, 28 bitop3:0x36
	v_lshrrev_b32_e32 v8, 3, v0
	v_lshlrev_b32_e32 v4, 11, v4
	v_lshlrev_b32_e32 v3, 4, v3
	v_and_b32_e32 v8, 2, v8
	v_bfe_u32 v9, v0, 1, 1
	v_lshlrev_b32_e32 v11, 4, v0
	v_and_b32_e32 v2, 63, v0
	v_and_b32_e32 v196, 31, v0
	v_and_or_b32 v3, v3, s97, v4
	v_and_b32_e32 v4, 15, v0
	v_bitop3_b32 v5, v195, v0, 15 bitop3:0x78
	v_or_b32_e32 v10, v8, v9
	v_and_b32_e32 v11, 0xc0, v11
	v_lshlrev_b32_e32 v0, 3, v0
	v_bitop3_b32 v8, v8, v195, v9 bitop3:0x36
	v_lshl_or_b32 v11, v195, 8, v11
	v_and_b32_e32 v0, 8, v0
	v_lshlrev_b32_e32 v8, 4, v8
	v_or3_b32 v207, v8, v11, v0
	v_bitop3_b32 v8, v195, v10, 2 bitop3:0x36
	s_add_i32 s7, s7, 0x12c00
	s_mov_b32 s8, m0
	s_mov_b32 m0, s7
	s_nop 0
	global_load_lds_dwordx4 v3, s[2:3]
	s_mov_b32 m0, s8
	v_bitop3_b32 v6, v195, v4, 2 bitop3:0x36
	v_bitop3_b32 v7, v195, v4, 4 bitop3:0x36
	v_bitop3_b32 v4, v195, v4, 6 bitop3:0x36
	v_lshlrev_b32_e32 v8, 4, v8
	s_lshl_b32 s2, s4, 9
	s_add_i32 s5, s5, s6
	v_lshlrev_b32_e32 v3, 8, v196
	v_lshlrev_b32_e32 v5, 4, v5
	v_lshlrev_b32_e32 v6, 4, v6
	v_lshlrev_b32_e32 v7, 4, v7
	v_lshlrev_b32_e32 v4, 4, v4
	s_add_i32 s78, s2, 0
	s_waitcnt vmcnt(0)
; #define ATT_LAS __attribute__((address_space(3)))
; __device__ __forceinline__ void attn_unit(ATT_LAS unsigned char* lds, const bf16_t* Qg, const bf16_t* Kg, const bf16_t* Vg, bf16_t* Og, int b, int head, int qb, float lam, const float* subg) {
;     ...
;     const ATT_LAS unsigned char* qbase = lds + QBUF + w * 8192;
;     int kaddr[4], vaddr[2];
; #pragma unroll
;     for (int ds = 0; ds < 4; ++ds) kaddr[ds] = koffs(r, 2 * ds + h);
;     { const int q = (lane & 15) >> 2, p = lane & 3, blk = (lane >> 4) & 1;
; #pragma unroll
;       for (int sub = 0; sub < 2; ++sub) vaddr[sub] = voffs(8 * sub + 4 * h + q, 2 * blk + (p >> 1)) + 8 * (p & 1); }
;     ATT_LAS float* wsf = (ATT_LAS float*)(lds + WSF + w * 512);
;     f32x16 O1[4], O2[4];
; #pragma unroll
;     for (int db = 0; db < 4; ++db)
; #pragma unroll
;         for (int i = 0; i < 16; ++i) { O1[db][i] = 0.f; O2[db][i] = 0.f; }
;     float m1 = -1e30f, m2 = -1e30f, l1 = 0.f, l2 = 0.f;
;     asm volatile("s_waitcnt vmcnt(0)" ::: "memory"); __syncthreads();
	v_lshlrev_b32_e32 v197, 2, v195
	v_or3_b32 v213, v8, v11, v0
	v_add_u32_e32 v0, s5, v196
	v_mov_b32_e32 v14, v1
	v_mov_b32_e32 v15, v1
	v_or_b32_e32 v203, v5, v3
	v_or_b32_e32 v204, v6, v3
	v_or_b32_e32 v205, v7, v3
	v_or_b32_e32 v206, v4, v3
	s_add_i32 s78, s78, 0x10000
	v_cmp_gt_u32_e64 s[2:3], 32, v2
	v_bitop3_b32 v209, v5, s98, v3 bitop3:0x36
	v_bitop3_b32 v210, v6, s98, v3 bitop3:0x36
	v_bitop3_b32 v211, v7, s98, v3 bitop3:0x36
	v_bitop3_b32 v212, v4, s98, v3 bitop3:0x36
	v_add_u32_e32 v244, s51, v209
	v_add_u32_e32 v245, s51, v210
	v_add_u32_e32 v246, s51, v211
	v_add_u32_e32 v247, s51, v212
	v_add_u32_e32 v217, s51, v203
	v_add_u32_e32 v219, s51, v204
	v_add_u32_e32 v221, s51, v205
	v_add_u32_e32 v223, s51, v206
	v_sub_u32_e32 v214, v0, v197
	v_mov_b32_e32 v0, v1
	v_mov_b32_e32 v2, v1
	v_mov_b32_e32 v3, v1
	v_mov_b32_e32 v4, v1
	v_mov_b32_e32 v5, v1
	v_mov_b32_e32 v6, v1
	v_mov_b32_e32 v7, v1
	v_mov_b32_e32 v8, v1
	v_mov_b32_e32 v9, v1
	v_mov_b32_e32 v10, v1
	v_mov_b32_e32 v11, v1
	v_mov_b32_e32 v12, v1
	v_mov_b32_e32 v13, v1
	v_mov_b64_e32 v[32:33], v[14:15]
	v_mov_b64_e32 v[112:113], v[14:15]
	v_mov_b64_e32 v[128:129], v[14:15]
	v_mov_b64_e32 v[144:145], v[14:15]
	v_mov_b64_e32 v[48:49], v[14:15]
	v_mov_b64_e32 v[64:65], v[14:15]
	v_mov_b64_e32 v[80:81], v[14:15]
	v_mov_b64_e32 v[96:97], v[14:15]
	v_lshl_add_u32 v202, v196, 2, s78
	v_lshlrev_b32_e32 v208, 4, v195
	s_mov_b32 s79, 0
	s_sub_i32 s80, 0, s5
	v_mov_b32_e32 v215, 0xf149f2ca
	v_mov_b32_e32 v224, 0
	s_mov_b64 s[92:93], s[86:87]
	s_mov_b64 s[94:95], s[70:71]
	v_mov_b64_e32 v[30:31], v[12:13]
	v_mov_b64_e32 v[28:29], v[10:11]
	v_mov_b64_e32 v[26:27], v[8:9]
	v_mov_b64_e32 v[24:25], v[6:7]
	v_mov_b64_e32 v[22:23], v[4:5]
	v_mov_b64_e32 v[20:21], v[2:3]
	v_mov_b64_e32 v[18:19], v[0:1]
	v_mov_b64_e32 v[110:111], v[12:13]
	v_mov_b64_e32 v[108:109], v[10:11]
	v_mov_b64_e32 v[106:107], v[8:9]
	v_mov_b64_e32 v[104:105], v[6:7]
	v_mov_b64_e32 v[102:103], v[4:5]
	v_mov_b64_e32 v[100:101], v[2:3]
	v_mov_b64_e32 v[98:99], v[0:1]
	v_mov_b64_e32 v[126:127], v[12:13]
	v_mov_b64_e32 v[124:125], v[10:11]
	v_mov_b64_e32 v[122:123], v[8:9]
	v_mov_b64_e32 v[120:121], v[6:7]
	v_mov_b64_e32 v[118:119], v[4:5]
	v_mov_b64_e32 v[116:117], v[2:3]
	v_mov_b64_e32 v[114:115], v[0:1]
	v_mov_b64_e32 v[142:143], v[12:13]
	v_mov_b64_e32 v[140:141], v[10:11]
	v_mov_b64_e32 v[138:139], v[8:9]
	v_mov_b64_e32 v[136:137], v[6:7]
	v_mov_b64_e32 v[134:135], v[4:5]
	v_mov_b64_e32 v[132:133], v[2:3]
	v_mov_b64_e32 v[130:131], v[0:1]
	v_mov_b64_e32 v[46:47], v[12:13]
	v_mov_b64_e32 v[44:45], v[10:11]
	v_mov_b64_e32 v[42:43], v[8:9]
	v_mov_b64_e32 v[40:41], v[6:7]
	v_mov_b64_e32 v[38:39], v[4:5]
	v_mov_b64_e32 v[36:37], v[2:3]
	v_mov_b64_e32 v[34:35], v[0:1]
	v_mov_b64_e32 v[62:63], v[12:13]
	v_mov_b64_e32 v[60:61], v[10:11]
	v_mov_b64_e32 v[58:59], v[8:9]
	v_mov_b64_e32 v[56:57], v[6:7]
	v_mov_b64_e32 v[54:55], v[4:5]
	v_mov_b64_e32 v[52:53], v[2:3]
	v_mov_b64_e32 v[50:51], v[0:1]
	v_mov_b64_e32 v[78:79], v[12:13]
	v_mov_b64_e32 v[76:77], v[10:11]
	v_mov_b64_e32 v[74:75], v[8:9]
	v_mov_b64_e32 v[72:73], v[6:7]
	v_mov_b64_e32 v[70:71], v[4:5]
	v_mov_b64_e32 v[68:69], v[2:3]
	v_mov_b64_e32 v[66:67], v[0:1]
	v_mov_b64_e32 v[94:95], v[12:13]
	v_mov_b64_e32 v[92:93], v[10:11]
	v_mov_b64_e32 v[90:91], v[8:9]
	v_mov_b64_e32 v[88:89], v[6:7]
	v_mov_b64_e32 v[86:87], v[4:5]
	v_mov_b64_e32 v[84:85], v[2:3]
	v_mov_b64_e32 v[82:83], v[0:1]
	v_mov_b32_e32 v225, 0
	v_mov_b32_e32 v0, 0xf149f2ca
	s_barrier
	s_branch .LBB0_289

; __device__ __forceinline__ void apply_mask(bool MASK, f32x16& s0, int kvr, int r, int h) {
;     if (MASK) {
;         asm volatile("" ::: "memory");
;         const int d = r - 4 * h - kvr;
; #pragma unroll
;         for (int i = 0; i < 16; ++i) { if (((i & 3) + 8 * (i >> 2)) > d) s0[i] = -INFINITY; }
;     }
; }
.Ldisp_check:
	v_or_b32_e32 v252, v0, v215
	v_cmp_eq_u32_e32 vcc, 0, v252
	s_cmp_eq_u64 vcc, exec
	s_cbranch_scc0 .Lorig_296
	s_mov_b32 s101, 1
	s_branch .Lns_296
.Lhead_mask:
	v_cmp_gt_i32_e32 vcc, 26, v214
	v_cmp_gt_i32_e64 s[34:35], 25, v214
	v_cmp_gt_i32_e64 s[28:29], 24, v214
	s_and_b64 s[34:35], vcc, s[34:35]
	v_cmp_gt_i32_e64 s[26:27], 19, v214
	s_and_b64 s[28:29], s[34:35], s[28:29]
	v_cmp_gt_i32_e64 s[24:25], 18, v214
	s_and_b64 s[26:27], s[28:29], s[26:27]
	v_cmp_gt_i32_e64 s[22:23], 17, v214
	s_and_b64 s[24:25], s[26:27], s[24:25]
	v_cmp_gt_i32_e64 s[20:21], 16, v214
	s_and_b64 s[22:23], s[24:25], s[22:23]
	v_cmp_gt_i32_e64 s[18:19], 11, v214
	s_and_b64 s[20:21], s[22:23], s[20:21]
	v_cmp_gt_i32_e64 s[16:17], 10, v214
	s_and_b64 s[18:19], s[20:21], s[18:19]
	v_cmp_gt_i32_e64 s[14:15], 9, v214
	s_and_b64 s[16:17], s[18:19], s[16:17]
	v_cmp_gt_i32_e64 s[12:13], 8, v214
	s_and_b64 s[14:15], s[16:17], s[14:15]
	v_cmp_gt_i32_e64 s[10:11], 3, v214
	s_and_b64 s[12:13], s[14:15], s[12:13]
	v_cmp_gt_i32_e64 s[8:9], 2, v214
	s_and_b64 s[10:11], s[12:13], s[10:11]
	v_cmp_gt_i32_e64 s[6:7], 1, v214
	s_and_b64 s[8:9], s[10:11], s[8:9]
	v_cmp_gt_i32_e64 s[4:5], 0, v214
	s_and_b64 s[6:7], s[8:9], s[6:7]
	s_and_b64 s[4:5], s[6:7], s[4:5]
	v_cndmask_b32_e64 v183, v183, v17, s[34:35]
	v_cndmask_b32_e64 v182, v182, v17, s[28:29]
	v_cndmask_b32_e64 v181, v181, v17, s[26:27]
	v_cndmask_b32_e64 v180, v180, v17, s[24:25]
	v_cndmask_b32_e64 v179, v179, v17, s[22:23]
	v_cndmask_b32_e64 v178, v178, v17, s[20:21]
	v_cndmask_b32_e64 v177, v177, v17, s[18:19]
	v_cndmask_b32_e64 v176, v176, v17, s[16:17]
	v_cndmask_b32_e64 v175, v175, v17, s[14:15]
	v_cndmask_b32_e64 v174, v174, v17, s[12:13]
	v_cndmask_b32_e64 v173, v173, v17, s[10:11]
	v_cndmask_b32_e64 v172, v172, v17, s[8:9]
	v_cndmask_b32_e64 v171, v171, v17, s[6:7]
	v_cndmask_b32_e64 v170, v170, v17, s[4:5]
	v_cndmask_b32_e32 v184, v184, v17, vcc
	v_cmp_gt_i32_e32 vcc, 27, v214
	s_and_saveexec_b64 s[4:5], vcc
	v_mov_b32_e32 v185, s31
	s_or_b64 exec, exec, s[4:5]
	s_branch .LBB0_296

; #define ATT_LAS __attribute__((address_space(3)))
; __device__ __forceinline__ void tile_body(bool MASK, const ATT_LAS unsigned char* kb, const ATT_LAS unsigned char* vb, const ATT_LAS unsigned char* qbase, const int (&kaddr)[4], const int (&vaddr)[2], ...
;     ...
;     qk_issue<false>(Sa, kb, qbase, kaddr);
;     apply_mask(MASK, Sa, kvrel, r, h); ls = l1;
; __device__ __forceinline__ void attn_unit(ATT_LAS unsigned char* lds, const bf16_t* Qg, const bf16_t* Kg, const bf16_t* Vg, bf16_t* Og, int b, int head, int qb, float lam, const float* subg) {
;     ...
;         const int kvrel = 64 * t - q0 - 32 * wq;
;         if (kvrel <= 31) {
;             const ATT_LAS unsigned char* kb = lds + KBUF + buf * 16384;
;             const ATT_LAS unsigned char* vb = lds + VBUF + buf * 16384;
;             tile_body(kvrel + 63 > 0, kb, vb, qbase, kaddr, vaddr, O1, O2, m1, m2, l1, l2, kvrel, r, h, wsf);
.LBB0_291:
	s_cmp_gt_i32 s80, 31
	s_cbranch_scc1 .Ldma_skip
	s_lshl_b32 s4, s4, 14
	s_add_i32 s81, s4, 0
	v_add_u32_e32 v248, s81, v209
	v_add_u32_e32 v249, s81, v210
	v_add_u32_e32 v250, s81, v211
	v_add_u32_e32 v251, s81, v212
	v_add_u32_e32 v216, s81, v203
	ds_read_b128 v[2:5], v216
	ds_read_b128 v[6:9], v217
	v_add_u32_e32 v218, s81, v204
	v_add_u32_e32 v220, s81, v205
	v_add_u32_e32 v222, s81, v206
	s_waitcnt lgkmcnt(0)
	v_mfma_f32_32x32x16_bf16 v[170:185], v[2:5], v[6:9], 0
	ds_read_b128 v[2:5], v218
	ds_read_b128 v[6:9], v219
	s_cmpk_gt_i32 s80, 0xffc1
	s_cselect_b64 s[36:37], -1, 0
	s_cmpk_lt_i32 s80, 0xffc2
	s_waitcnt lgkmcnt(0)
	v_mfma_f32_32x32x16_bf16 v[170:185], v[2:5], v[6:9], v[170:185]
	ds_read_b128 v[2:5], v220
	ds_read_b128 v[6:9], v221
	s_waitcnt lgkmcnt(0)
	v_mfma_f32_32x32x16_bf16 v[170:185], v[2:5], v[6:9], v[170:185]
	ds_read_b128 v[2:5], v222
	ds_read_b128 v[6:9], v223
	s_waitcnt lgkmcnt(0)
	v_mfma_f32_32x32x16_bf16 v[170:185], v[2:5], v[6:9], v[170:185]
	s_cbranch_scc0 .Lhead_mask

; __device__ __forceinline__ void tile_body(bool MASK, const ATT_LAS unsigned char* kb, const ATT_LAS unsigned char* vb, const ATT_LAS unsigned char* qbase, const int (&kaddr)[4], const int (&vaddr)[2], ...
;     f32x16 Sa, Sb; u32x4 pkA[2], pkB[2]; float ls, sm;
;     qk_issue<false>(Sa, kb, qbase, kaddr);
;     apply_mask(MASK, Sa, kvrel, r, h); ls = l1;
;     sm = step_fused<false, true, true>(Sa, m1, l1, pkA, O1, pkA, vb, vaddr, Sb, kb, qbase, kaddr);
;     if (__any(!(sm <= GUARD))) slow_step<false>(MASK, Sa, kb, qbase, kaddr, vaddr, O1, m1, l1, ls, kvrel, r, h, wsf, pkA);
.Ldma_s1:
	s_cmp_eq_u32 s101, 1
	s_cbranch_scc0 .Ldisp_check

; #define ATT_LAS __attribute__((address_space(3)))
; __device__ __forceinline__ s16x4 vtr(const ATT_LAS unsigned char* p) { return __builtin_bit_cast(s16x4, __builtin_amdgcn_ds_read_tr16_b64_v4i16((ATT_LAS s16x4*)p)); }
; #define ATT_MFMA(a, b, c) __builtin_amdgcn_mfma_f32_32x32x16_bf16((a), (b), (c), 0, 0, 0)
; __device__ __forceinline__ void pv_issue(f32x16 (&O)[4], const u32x4 (&pk)[2], const ATT_LAS unsigned char* vb, const int (&vaddr)[2]) {
; #pragma unroll
;     for (int s_ = 0; s_ < 2; ++s_) { const bf16x8 pa = __builtin_bit_cast(bf16x8, pk[s_]);
; #pragma unroll
;         for (int db = 0; db < 4; ++db) {
;             const s16x4 lo = vtr(vb + vaddr[0] + db * 512 + s_ * 4096), hi = vtr(vb + vaddr[1] + db * 512 + s_ * 4096);
;             const bf16x8 vf = __builtin_shufflevector(lo, hi, 0, 1, 2, 3, 4, 5, 6, 7);
;             O[db] = ATT_MFMA(pa, vf, O[db]); } }
; }
; __device__ __forceinline__ void tile_body(bool MASK, const ATT_LAS unsigned char* kb, const ATT_LAS unsigned char* vb, const ATT_LAS unsigned char* qbase, const int (&kaddr)[4], const int (&vaddr)[2], ...
;     ...
;     pv_issue(O2, pkB, vb + 8192, vaddr);
; __device__ __forceinline__ void attn_unit(ATT_LAS unsigned char* lds, const bf16_t* Qg, const bf16_t* Kg, const bf16_t* Vg, bf16_t* Og, int b, int head, int qb, float lam, const float* subg) {
;     ...
;         asm volatile("s_waitcnt vmcnt(0)" ::: "memory"); __syncthreads();
.Lns_341:
	ds_read_b64_tr_b16 v[8:9], v178 offset:43008
	ds_read_b64_tr_b16 v[6:7], v179 offset:40960
	ds_read_b64_tr_b16 v[146:147], v179 offset:41472
	ds_read_b64_tr_b16 v[150:151], v179 offset:41984
	ds_read_b64_tr_b16 v[154:155], v179 offset:42496
	ds_read_b64_tr_b16 v[148:149], v178 offset:43520
	ds_read_b64_tr_b16 v[152:153], v178 offset:44032
	ds_read_b64_tr_b16 v[156:157], v178 offset:44544
	s_waitcnt lgkmcnt(6)
	v_mfma_f32_32x32x16_bf16 v[34:49], v[2:5], v[6:9], v[34:49]
	v_exp_f32_e32 v15, v162
	v_exp_f32_e32 v14, v163
	v_exp_f32_e32 v163, v164
	s_waitcnt lgkmcnt(2)
	v_mfma_f32_32x32x16_bf16 v[50:65], v[2:5], v[146:149], v[50:65]
	v_exp_f32_e32 v162, v165
	s_waitcnt lgkmcnt(1)
	v_mfma_f32_32x32x16_bf16 v[66:81], v[2:5], v[150:153], v[66:81]
	ds_read_b64_tr_b16 v[146:147], v179 offset:45056
	ds_read_b64_tr_b16 v[148:149], v178 offset:47104
	ds_read_b64_tr_b16 v[160:161], v178 offset:47616
	ds_read_b64_tr_b16 v[158:159], v179 offset:45568
	v_exp_f32_e32 v165, v166
	v_exp_f32_e32 v164, v167
	v_exp_f32_e32 v167, v168
	s_waitcnt lgkmcnt(4)
	v_mfma_f32_32x32x16_bf16 v[82:97], v[2:5], v[154:157], v[82:97]
	v_exp_f32_e32 v166, v169
	v_cvt_pk_bf16_f32 v6, v15, v14
	v_cvt_pk_bf16_f32 v7, v163, v162
	v_cvt_pk_bf16_f32 v8, v165, v164
	v_cvt_pk_bf16_f32 v9, v167, v166
	s_waitcnt lgkmcnt(2)
	v_mfma_f32_32x32x16_bf16 v[34:49], v[10:13], v[146:149], v[34:49]
	ds_read_b64_tr_b16 v[2:3], v179 offset:46080
	ds_read_b64_tr_b16 v[4:5], v178 offset:48128
	ds_read_b64_tr_b16 v[152:153], v178 offset:48640
	ds_read_b64_tr_b16 v[150:151], v179 offset:46592
	v_exp_f32_e32 v147, v170
	v_exp_f32_e32 v146, v171
	v_exp_f32_e32 v149, v172
	s_waitcnt lgkmcnt(4)
	v_mfma_f32_32x32x16_bf16 v[50:65], v[10:13], v[158:161], v[50:65]
	v_exp_f32_e32 v148, v173
	s_waitcnt lgkmcnt(2)
	v_mfma_f32_32x32x16_bf16 v[66:81], v[10:13], v[2:5], v[66:81]
	v_exp_f32_e32 v155, v174
	v_exp_f32_e32 v154, v175
	v_exp_f32_e32 v157, v176
	s_waitcnt lgkmcnt(0)
	v_mfma_f32_32x32x16_bf16 v[82:97], v[10:13], v[150:153], v[82:97]
	v_add_f32_e64 v10, v162, v14
	v_add_f32_e64 v11, v163, v15
	v_exp_f32_e32 v156, v177
	v_add_f32_e32 v10, v164, v10
	v_add_f32_e32 v11, v165, v11
	v_cvt_pk_bf16_f32 v2, v147, v146
	v_cvt_pk_bf16_f32 v3, v149, v148
	v_cvt_pk_bf16_f32 v4, v155, v154
	v_cvt_pk_bf16_f32 v5, v157, v156
	v_add_f32_e32 v10, v166, v10
	v_add_f32_e32 v11, v167, v11
	v_add_f32_e32 v10, v146, v10
	v_add_f32_e32 v11, v147, v11
	v_add_f32_e32 v10, v148, v10
	v_add_f32_e32 v11, v149, v11
	v_add_f32_e32 v10, v154, v10
	v_add_f32_e32 v11, v155, v11
	v_add_f32_e32 v10, v156, v10
	v_add_f32_e32 v11, v157, v11
	v_add_f32_e32 v10, v10, v11
	v_cmp_nge_f32_e32 vcc, s58, v10
	s_cbranch_vccnz .Lslow_4
	v_add_f32_e32 v224, v181, v10
	ds_read_b64_tr_b16 v[12:13], v178 offset:43008
	ds_read_b64_tr_b16 v[10:11], v179 offset:40960
	ds_read_b64_tr_b16 v[146:147], v179 offset:41472
	ds_read_b64_tr_b16 v[150:151], v179 offset:41984
	ds_read_b64_tr_b16 v[154:155], v179 offset:42496
	ds_read_b64_tr_b16 v[148:149], v178 offset:43520
	ds_read_b64_tr_b16 v[152:153], v178 offset:44032
	ds_read_b64_tr_b16 v[156:157], v178 offset:44544
	ds_read_b64_tr_b16 v[160:161], v178 offset:47104
	ds_read_b64_tr_b16 v[158:159], v179 offset:45056
	ds_read_b64_tr_b16 v[162:163], v179 offset:45568
	ds_read_b64_tr_b16 v[166:167], v179 offset:46080
	ds_read_b64_tr_b16 v[170:171], v179 offset:46592
	ds_read_b64_tr_b16 v[164:165], v178 offset:47616
	ds_read_b64_tr_b16 v[168:169], v178 offset:48128
	s_waitcnt lgkmcnt(7)
	v_mfma_f32_32x32x16_bf16 v[130:145], v[6:9], v[10:13], v[130:145]
	v_mfma_f32_32x32x16_bf16 v[114:129], v[6:9], v[146:149], v[114:129]
	v_mfma_f32_32x32x16_bf16 v[98:113], v[6:9], v[150:153], v[98:113]
	v_mfma_f32_32x32x16_bf16 v[18:33], v[6:9], v[154:157], v[18:33]
	ds_read_b64_tr_b16 v[172:173], v178 offset:48640
	s_waitcnt lgkmcnt(0)
	v_mfma_f32_32x32x16_bf16 v[130:145], v[2:5], v[158:161], v[130:145]
	v_mfma_f32_32x32x16_bf16 v[114:129], v[2:5], v[162:165], v[114:129]
	v_mfma_f32_32x32x16_bf16 v[98:113], v[2:5], v[166:169], v[98:113]
	v_mfma_f32_32x32x16_bf16 v[18:33], v[2:5], v[170:173], v[18:33]
	s_add_i32 s80, s80, 64
	s_add_u32 s94, s94, 0x20000
	s_addc_u32 s95, s95, 0
	s_waitcnt vmcnt(0)
	s_add_u32 s92, s92, 0x20000
	s_addc_u32 s93, s93, 0
	s_cmp_eq_u32 s76, s79
	v_subrev_u32_e32 v214, 64, v214
	s_barrier
	s_cbranch_scc0 .LBB0_289
	s_branch .LBB0_352

; #define ATT_LAS __attribute__((address_space(3)))
; __device__ __forceinline__ void rowmax_rescale(bool MASK, f32x16& s0, f32x16 (&O)[4], float& m, float& l, int kvr, int r, int h, ATT_LAS float* wsf) {
;     if (MASK) {
;         asm volatile("" ::: "memory");
;         const int d = r - 4 * h - kvr;
; #pragma unroll
;         for (int i = 0; i < 16; ++i) { if (((i & 3) + 8 * (i >> 2)) > d) s0[i] = -INFINITY; }
;     }
; template <bool C1> __device__ __forceinline__ void slow_step(bool MASK, f32x16& S, const ATT_LAS unsigned char* kb, const ATT_LAS unsigned char* qbase, const int (&kaddr)[4], const int (&vaddr)[2], ...
;     l = l_saved;
;     qk_issue<C1>(S, kb, qbase, kaddr);
;     rowmax_rescale(MASK, S, O, m, l, kvr, r, h, wsf);
;     f32x16 dummy;
;     step_fused<false, false, false>(S, m, l, pk, O, pk, kb, vaddr, dummy, kb, qbase, kaddr);
; }
.Lslow_1:
	s_mov_b32 s101, 0
	ds_read_b128 v[2:5], v216
	ds_read_b128 v[6:9], v217
	s_and_b64 vcc, exec, s[4:5]
	s_waitcnt lgkmcnt(0)
	v_mfma_f32_32x32x16_bf16 v[174:189], v[2:5], v[6:9], 0
	ds_read_b128 v[2:5], v218
	ds_read_b128 v[6:9], v219
	s_waitcnt lgkmcnt(0)
	v_mfma_f32_32x32x16_bf16 v[174:189], v[2:5], v[6:9], v[174:189]
	ds_read_b128 v[2:5], v220
	ds_read_b128 v[6:9], v221
	s_waitcnt lgkmcnt(0)
	v_mfma_f32_32x32x16_bf16 v[174:189], v[2:5], v[6:9], v[174:189]
	ds_read_b128 v[2:5], v222
	ds_read_b128 v[6:9], v223
	s_waitcnt lgkmcnt(0)
	v_mfma_f32_32x32x16_bf16 v[174:189], v[2:5], v[6:9], v[174:189]
	s_cbranch_vccnz .LBB0_301
	v_cmp_gt_i32_e32 vcc, 27, v214
	s_and_saveexec_b64 s[36:37], vcc
	s_cbranch_execz .LBB0_300
	v_cmp_gt_i32_e32 vcc, 24, v214
	v_cmp_gt_i32_e64 s[34:35], 25, v214
	v_cmp_gt_i32_e64 s[6:7], 19, v214
	s_and_b64 vcc, s[34:35], vcc
	v_cmp_gt_i32_e64 s[8:9], 18, v214
	s_nop 2
	v_cndmask_b32_e32 v3, v186, v17, vcc
	s_and_b64 vcc, vcc, s[6:7]
	v_cmp_gt_i32_e64 s[10:11], 17, v214
	v_cndmask_b32_e32 v4, v185, v17, vcc
	s_and_b64 vcc, vcc, s[8:9]
	v_cmp_gt_i32_e64 s[12:13], 16, v214
	v_cndmask_b32_e32 v5, v184, v17, vcc
	s_and_b64 vcc, vcc, s[10:11]
	v_cmp_gt_i32_e64 s[14:15], 11, v214
	v_cndmask_b32_e32 v6, v183, v17, vcc
	s_and_b64 vcc, vcc, s[12:13]
	v_cmp_gt_i32_e64 s[16:17], 10, v214
	v_cndmask_b32_e32 v7, v182, v17, vcc
	s_and_b64 vcc, vcc, s[14:15]
	v_cmp_gt_i32_e64 s[18:19], 9, v214
	v_cndmask_b32_e32 v8, v181, v17, vcc
	s_and_b64 vcc, vcc, s[16:17]
	v_cmp_gt_i32_e64 s[20:21], 8, v214
	v_cndmask_b32_e32 v16, v180, v17, vcc
	s_and_b64 vcc, vcc, s[18:19]
	v_cmp_gt_i32_e64 s[22:23], 3, v214
	v_cndmask_b32_e32 v146, v179, v17, vcc
	s_and_b64 vcc, vcc, s[20:21]
	v_cmp_gt_i32_e64 s[24:25], 2, v214
	v_cndmask_b32_e32 v147, v178, v17, vcc
	s_and_b64 vcc, vcc, s[22:23]
	v_cmp_gt_i32_e64 s[26:27], 1, v214
	v_cndmask_b32_e32 v148, v177, v17, vcc
	s_and_b64 vcc, vcc, s[24:25]
	v_cmp_gt_i32_e64 s[28:29], 0, v214
	v_cndmask_b32_e32 v149, v176, v17, vcc
	s_and_b64 vcc, vcc, s[26:27]
	v_cndmask_b32_e32 v150, v175, v17, vcc
	s_and_b64 vcc, vcc, s[28:29]
	v_cndmask_b32_e32 v151, v174, v17, vcc
	v_cmp_eq_u32_e32 vcc, 26, v214
	v_cndmask_b32_e64 v2, v187, v17, s[34:35]
	s_nop 0
	v_cndmask_b32_e32 v9, v8, v181, vcc
	v_cndmask_b32_e32 v8, v16, v180, vcc
	v_cndmask_b32_e32 v16, v17, v188, vcc
	v_cndmask_b32_e32 v15, v2, v187, vcc
	v_cndmask_b32_e32 v14, v3, v186, vcc
	v_cndmask_b32_e32 v13, v4, v185, vcc
	v_cndmask_b32_e32 v12, v5, v184, vcc
	v_cndmask_b32_e32 v11, v6, v183, vcc
	v_cndmask_b32_e32 v10, v7, v182, vcc
	v_cndmask_b32_e32 v7, v146, v179, vcc
	v_cndmask_b32_e32 v6, v147, v178, vcc
	v_cndmask_b32_e32 v5, v148, v177, vcc
	v_cndmask_b32_e32 v4, v149, v176, vcc
	v_cndmask_b32_e32 v3, v150, v175, vcc
	v_cndmask_b32_e32 v2, v151, v174, vcc
	v_mov_b64_e32 v[188:189], v[16:17]
	v_mov_b64_e32 v[186:187], v[14:15]
	v_mov_b64_e32 v[184:185], v[12:13]
	v_mov_b64_e32 v[182:183], v[10:11]
	v_mov_b64_e32 v[180:181], v[8:9]
	v_mov_b64_e32 v[178:179], v[6:7]
	v_mov_b64_e32 v[176:177], v[4:5]
	v_mov_b64_e32 v[174:175], v[2:3]

; #define ATT_LAS __attribute__((address_space(3)))
; __device__ __forceinline__ void rowmax_rescale(bool MASK, f32x16& s0, f32x16 (&O)[4], float& m, float& l, int kvr, int r, int h, ATT_LAS float* wsf) {
;     if (MASK) {
;         asm volatile("" ::: "memory");
;         const int d = r - 4 * h - kvr;
; #pragma unroll
;         for (int i = 0; i < 16; ++i) { if (((i & 3) + 8 * (i >> 2)) > d) s0[i] = -INFINITY; }
;     }
; template <bool C1> __device__ __forceinline__ void slow_step(bool MASK, f32x16& S, const ATT_LAS unsigned char* kb, const ATT_LAS unsigned char* qbase, const int (&kaddr)[4], const int (&vaddr)[2], ...
;     l = l_saved;
;     qk_issue<C1>(S, kb, qbase, kaddr);
;     rowmax_rescale(MASK, S, O, m, l, kvr, r, h, wsf);
;     f32x16 dummy;
;     step_fused<false, false, false>(S, m, l, pk, O, pk, kb, vaddr, dummy, kb, qbase, kaddr);
; }
.Lslow_2:
	s_mov_b32 s101, 0
	v_mov_b32_e32 v6, v209
	v_mov_b32_e32 v10, v210
	v_add_u32_e32 v2, s81, v6
	ds_read_b128 v[2:5], v2
	v_add_u32_e32 v6, s51, v6
	ds_read_b128 v[6:9], v6
	s_and_b64 vcc, exec, s[4:5]
	v_add_u32_e32 v11, s81, v10
	s_waitcnt lgkmcnt(0)
	v_mfma_f32_32x32x16_bf16 v[162:177], v[2:5], v[6:9], 0
	ds_read_b128 v[2:5], v11
	v_add_u32_e32 v6, s51, v10
	ds_read_b128 v[6:9], v6
	v_mov_b32_e32 v10, v211
	s_nop 0
	v_add_u32_e32 v11, s81, v10
	s_waitcnt lgkmcnt(0)
	v_mfma_f32_32x32x16_bf16 v[162:177], v[2:5], v[6:9], v[162:177]
	ds_read_b128 v[2:5], v11
	v_add_u32_e32 v6, s51, v10
	ds_read_b128 v[6:9], v6
	v_mov_b32_e32 v10, v212
	s_nop 0
	v_add_u32_e32 v11, s81, v10
	s_waitcnt lgkmcnt(0)
	v_mfma_f32_32x32x16_bf16 v[162:177], v[2:5], v[6:9], v[162:177]
	ds_read_b128 v[2:5], v11
	v_add_u32_e32 v6, s51, v10
	ds_read_b128 v[6:9], v6
	s_waitcnt lgkmcnt(0)
	v_mfma_f32_32x32x16_bf16 v[162:177], v[2:5], v[6:9], v[162:177]
	s_cbranch_vccnz .LBB0_316
	v_cmp_gt_i32_e32 vcc, 27, v214
	s_and_saveexec_b64 s[36:37], vcc
	s_cbranch_execz .LBB0_315
	v_cmp_gt_i32_e32 vcc, 24, v214
	v_cmp_gt_i32_e64 s[34:35], 25, v214
	v_cmp_gt_i32_e64 s[6:7], 19, v214
	s_and_b64 vcc, s[34:35], vcc
	v_cmp_gt_i32_e64 s[8:9], 18, v214
	s_nop 2
	v_cndmask_b32_e32 v3, v174, v17, vcc
	s_and_b64 vcc, vcc, s[6:7]
	v_cmp_gt_i32_e64 s[10:11], 17, v214
	v_cndmask_b32_e32 v4, v173, v17, vcc
	s_and_b64 vcc, vcc, s[8:9]
	v_cmp_gt_i32_e64 s[12:13], 16, v214
	v_cndmask_b32_e32 v5, v172, v17, vcc
	s_and_b64 vcc, vcc, s[10:11]
	v_cmp_gt_i32_e64 s[14:15], 11, v214
	v_cndmask_b32_e32 v6, v171, v17, vcc
	s_and_b64 vcc, vcc, s[12:13]
	v_cmp_gt_i32_e64 s[16:17], 10, v214
	v_cndmask_b32_e32 v7, v170, v17, vcc
	s_and_b64 vcc, vcc, s[14:15]
	v_cmp_gt_i32_e64 s[18:19], 9, v214
	v_cndmask_b32_e32 v8, v169, v17, vcc
	s_and_b64 vcc, vcc, s[16:17]
	v_cmp_gt_i32_e64 s[20:21], 8, v214
	v_cndmask_b32_e32 v16, v168, v17, vcc
	s_and_b64 vcc, vcc, s[18:19]
	v_cmp_gt_i32_e64 s[22:23], 3, v214
	v_cndmask_b32_e32 v177, v167, v17, vcc
	s_and_b64 vcc, vcc, s[20:21]
	v_cmp_gt_i32_e64 s[24:25], 2, v214
	v_cndmask_b32_e32 v181, v166, v17, vcc
	s_and_b64 vcc, vcc, s[22:23]
	v_cmp_gt_i32_e64 s[26:27], 1, v214
	v_cndmask_b32_e32 v182, v165, v17, vcc
	s_and_b64 vcc, vcc, s[24:25]
	v_cmp_gt_i32_e64 s[28:29], 0, v214
	v_cndmask_b32_e32 v183, v164, v17, vcc
	s_and_b64 vcc, vcc, s[26:27]
	v_cndmask_b32_e32 v184, v163, v17, vcc
	s_and_b64 vcc, vcc, s[28:29]
	v_cndmask_b32_e32 v185, v162, v17, vcc
	v_cmp_eq_u32_e32 vcc, 26, v214
	v_cndmask_b32_e64 v2, v175, v17, s[34:35]
	s_nop 0
	v_cndmask_b32_e32 v9, v8, v169, vcc
	v_cndmask_b32_e32 v8, v16, v168, vcc
	v_cndmask_b32_e32 v16, v17, v176, vcc
	v_cndmask_b32_e32 v15, v2, v175, vcc
	v_cndmask_b32_e32 v14, v3, v174, vcc
	v_cndmask_b32_e32 v13, v4, v173, vcc
	v_cndmask_b32_e32 v12, v5, v172, vcc
	v_cndmask_b32_e32 v11, v6, v171, vcc
	v_cndmask_b32_e32 v10, v7, v170, vcc
	v_cndmask_b32_e32 v7, v177, v167, vcc
	v_cndmask_b32_e32 v6, v181, v166, vcc
	v_cndmask_b32_e32 v5, v182, v165, vcc
	v_cndmask_b32_e32 v4, v183, v164, vcc
	v_cndmask_b32_e32 v3, v184, v163, vcc
	v_cndmask_b32_e32 v2, v185, v162, vcc
	v_mov_b64_e32 v[176:177], v[16:17]
	v_mov_b64_e32 v[174:175], v[14:15]
	v_mov_b64_e32 v[172:173], v[12:13]
	v_mov_b64_e32 v[170:171], v[10:11]
	v_mov_b64_e32 v[168:169], v[8:9]
	v_mov_b64_e32 v[166:167], v[6:7]
	v_mov_b64_e32 v[164:165], v[4:5]
	v_mov_b64_e32 v[162:163], v[2:3]

; #define ATT_LAS __attribute__((address_space(3)))
; __device__ __forceinline__ void rowmax_rescale(bool MASK, f32x16& s0, f32x16 (&O)[4], float& m, float& l, int kvr, int r, int h, ATT_LAS float* wsf) {
;     if (MASK) {
;         asm volatile("" ::: "memory");
;         const int d = r - 4 * h - kvr;
; #pragma unroll
;         for (int i = 0; i < 16; ++i) { if (((i & 3) + 8 * (i >> 2)) > d) s0[i] = -INFINITY; }
;     }
; template <bool C1> __device__ __forceinline__ void slow_step(bool MASK, f32x16& S, const ATT_LAS unsigned char* kb, const ATT_LAS unsigned char* qbase, const int (&kaddr)[4], const int (&vaddr)[2], ...
;     l = l_saved;
;     qk_issue<C1>(S, kb, qbase, kaddr);
;     rowmax_rescale(MASK, S, O, m, l, kvr, r, h, wsf);
;     f32x16 dummy;
;     step_fused<false, false, false>(S, m, l, pk, O, pk, kb, vaddr, dummy, kb, qbase, kaddr);
; }
.Lslow_3:
	s_mov_b32 s101, 0
	ds_read_b128 v[2:5], v216 offset:8192
	ds_read_b128 v[6:9], v217
	s_and_b64 vcc, exec, s[4:5]
	s_waitcnt lgkmcnt(0)
	v_mfma_f32_32x32x16_bf16 v[146:161], v[2:5], v[6:9], 0
	ds_read_b128 v[2:5], v218 offset:8192
	ds_read_b128 v[6:9], v219
	s_waitcnt lgkmcnt(0)
	v_mfma_f32_32x32x16_bf16 v[146:161], v[2:5], v[6:9], v[146:161]
	ds_read_b128 v[2:5], v220 offset:8192
	ds_read_b128 v[6:9], v221
	s_waitcnt lgkmcnt(0)
	v_mfma_f32_32x32x16_bf16 v[146:161], v[2:5], v[6:9], v[146:161]
	ds_read_b128 v[2:5], v222 offset:8192
	ds_read_b128 v[6:9], v223
	s_waitcnt lgkmcnt(0)
	v_mfma_f32_32x32x16_bf16 v[146:161], v[2:5], v[6:9], v[146:161]
	s_cbranch_vccnz .LBB0_331
	v_subrev_u32_e32 v2, 32, v214
	v_cmp_gt_i32_e32 vcc, 27, v2
	s_and_saveexec_b64 s[36:37], vcc
	s_cbranch_execz .LBB0_330
	v_cmp_gt_i32_e32 vcc, 24, v2
	v_cmp_gt_i32_e64 s[34:35], 25, v2
	v_cmp_gt_i32_e64 s[6:7], 19, v2
	s_and_b64 vcc, s[34:35], vcc
	v_cmp_gt_i32_e64 s[8:9], 18, v2
	s_nop 1
	v_cndmask_b32_e32 v3, v158, v17, vcc
	s_and_b64 vcc, vcc, s[6:7]
	v_cmp_gt_i32_e64 s[10:11], 17, v2
	v_cndmask_b32_e32 v4, v157, v17, vcc
	s_and_b64 vcc, vcc, s[8:9]
	v_cmp_gt_i32_e64 s[12:13], 16, v2
	v_cndmask_b32_e32 v5, v156, v17, vcc
	s_and_b64 vcc, vcc, s[10:11]
	v_cmp_gt_i32_e64 s[14:15], 11, v2
	v_cndmask_b32_e32 v6, v155, v17, vcc
	s_and_b64 vcc, vcc, s[12:13]
	v_cmp_gt_i32_e64 s[16:17], 10, v2
	v_cndmask_b32_e32 v7, v154, v17, vcc
	s_and_b64 vcc, vcc, s[14:15]
	v_cmp_gt_i32_e64 s[18:19], 9, v2
	v_cndmask_b32_e32 v8, v153, v17, vcc
	s_and_b64 vcc, vcc, s[16:17]
	v_cmp_gt_i32_e64 s[20:21], 8, v2
	v_cndmask_b32_e32 v16, v152, v17, vcc
	s_and_b64 vcc, vcc, s[18:19]
	v_cmp_gt_i32_e64 s[22:23], 3, v2
	v_cndmask_b32_e32 v161, v151, v17, vcc
	s_and_b64 vcc, vcc, s[20:21]
	v_cmp_gt_i32_e64 s[24:25], 2, v2
	v_cndmask_b32_e32 v182, v150, v17, vcc
	s_and_b64 vcc, vcc, s[22:23]
	v_cmp_gt_i32_e64 s[26:27], 1, v2
	v_cndmask_b32_e32 v183, v149, v17, vcc
	s_and_b64 vcc, vcc, s[24:25]
	v_cmp_gt_i32_e64 s[28:29], 0, v2
	v_cndmask_b32_e32 v184, v148, v17, vcc
	s_and_b64 vcc, vcc, s[26:27]
	v_cndmask_b32_e32 v185, v147, v17, vcc
	s_and_b64 vcc, vcc, s[28:29]
	v_cndmask_b32_e32 v186, v146, v17, vcc
	v_cmp_eq_u32_e32 vcc, 58, v214
	v_cndmask_b32_e64 v2, v159, v17, s[34:35]
	s_nop 0
	v_cndmask_b32_e32 v9, v8, v153, vcc
	v_cndmask_b32_e32 v8, v16, v152, vcc
	v_cndmask_b32_e32 v16, v17, v160, vcc
	v_cndmask_b32_e32 v15, v2, v159, vcc
	v_cndmask_b32_e32 v14, v3, v158, vcc
	v_cndmask_b32_e32 v13, v4, v157, vcc
	v_cndmask_b32_e32 v12, v5, v156, vcc
	v_cndmask_b32_e32 v11, v6, v155, vcc
	v_cndmask_b32_e32 v10, v7, v154, vcc
	v_cndmask_b32_e32 v7, v161, v151, vcc
	v_cndmask_b32_e32 v6, v182, v150, vcc
	v_cndmask_b32_e32 v5, v183, v149, vcc
	v_cndmask_b32_e32 v4, v184, v148, vcc
	v_cndmask_b32_e32 v3, v185, v147, vcc
	v_cndmask_b32_e32 v2, v186, v146, vcc
	v_mov_b64_e32 v[160:161], v[16:17]
	v_mov_b64_e32 v[158:159], v[14:15]
	v_mov_b64_e32 v[156:157], v[12:13]
	v_mov_b64_e32 v[154:155], v[10:11]
	v_mov_b64_e32 v[152:153], v[8:9]
	v_mov_b64_e32 v[150:151], v[6:7]
	v_mov_b64_e32 v[148:149], v[4:5]
	v_mov_b64_e32 v[146:147], v[2:3]

; #define ATT_LAS __attribute__((address_space(3)))
; __device__ __forceinline__ void rowmax_rescale(bool MASK, f32x16& s0, f32x16 (&O)[4], float& m, float& l, int kvr, int r, int h, ATT_LAS float* wsf) {
;     if (MASK) {
;         asm volatile("" ::: "memory");
;         const int d = r - 4 * h - kvr;
; #pragma unroll
;         for (int i = 0; i < 16; ++i) { if (((i & 3) + 8 * (i >> 2)) > d) s0[i] = -INFINITY; }
;     }
; template <bool C1> __device__ __forceinline__ void slow_step(bool MASK, f32x16& S, const ATT_LAS unsigned char* kb, const ATT_LAS unsigned char* qbase, const int (&kaddr)[4], const int (&vaddr)[2], ...
;     l = l_saved;
;     qk_issue<C1>(S, kb, qbase, kaddr);
;     rowmax_rescale(MASK, S, O, m, l, kvr, r, h, wsf);
;     f32x16 dummy;
;     step_fused<false, false, false>(S, m, l, pk, O, pk, kb, vaddr, dummy, kb, qbase, kaddr);
; }
.Lslow_4:
	s_mov_b32 s101, 0
	v_mov_b32_e32 v6, v209
	v_mov_b32_e32 v10, v210
	v_add_u32_e32 v2, s81, v6
	ds_read_b128 v[2:5], v2 offset:8192
	v_add_u32_e32 v6, s51, v6
	ds_read_b128 v[6:9], v6
	s_and_b64 vcc, exec, s[4:5]
	v_add_u32_e32 v11, s81, v10
	s_waitcnt lgkmcnt(0)
	v_mfma_f32_32x32x16_bf16 v[146:161], v[2:5], v[6:9], 0
	ds_read_b128 v[2:5], v11 offset:8192
	v_add_u32_e32 v6, s51, v10
	ds_read_b128 v[6:9], v6
	v_mov_b32_e32 v10, v211
	s_nop 0
	v_add_u32_e32 v11, s81, v10
	s_waitcnt lgkmcnt(0)
	v_mfma_f32_32x32x16_bf16 v[146:161], v[2:5], v[6:9], v[146:161]
	ds_read_b128 v[2:5], v11 offset:8192
	v_add_u32_e32 v6, s51, v10
	ds_read_b128 v[6:9], v6
	v_mov_b32_e32 v10, v212
	s_nop 0
	v_add_u32_e32 v11, s81, v10
	s_waitcnt lgkmcnt(0)
	v_mfma_f32_32x32x16_bf16 v[146:161], v[2:5], v[6:9], v[146:161]
	ds_read_b128 v[2:5], v11 offset:8192
	v_add_u32_e32 v6, s51, v10
	ds_read_b128 v[6:9], v6
	s_waitcnt lgkmcnt(0)
	v_mfma_f32_32x32x16_bf16 v[146:161], v[2:5], v[6:9], v[146:161]
	s_cbranch_vccnz .LBB0_346
	v_subrev_u32_e32 v2, 32, v214
	v_cmp_gt_i32_e32 vcc, 27, v2
	s_and_saveexec_b64 s[34:35], vcc
	s_cbranch_execz .LBB0_345
	v_cmp_gt_i32_e32 vcc, 24, v2
	v_cmp_gt_i32_e64 s[28:29], 25, v2
	v_cmp_gt_i32_e64 s[4:5], 19, v2
	s_and_b64 vcc, s[28:29], vcc
	v_cmp_gt_i32_e64 s[6:7], 18, v2
	s_nop 1
	v_cndmask_b32_e32 v3, v158, v17, vcc
	s_and_b64 vcc, vcc, s[4:5]
	v_cmp_gt_i32_e64 s[8:9], 17, v2
	v_cndmask_b32_e32 v4, v157, v17, vcc
	s_and_b64 vcc, vcc, s[6:7]
	v_cmp_gt_i32_e64 s[10:11], 16, v2
	v_cndmask_b32_e32 v5, v156, v17, vcc
	s_and_b64 vcc, vcc, s[8:9]
	v_cmp_gt_i32_e64 s[12:13], 11, v2
	v_cndmask_b32_e32 v6, v155, v17, vcc
	s_and_b64 vcc, vcc, s[10:11]
	v_cmp_gt_i32_e64 s[14:15], 10, v2
	v_cndmask_b32_e32 v7, v154, v17, vcc
	s_and_b64 vcc, vcc, s[12:13]
	v_cmp_gt_i32_e64 s[16:17], 9, v2
	v_cndmask_b32_e32 v8, v153, v17, vcc
	s_and_b64 vcc, vcc, s[14:15]
	v_cmp_gt_i32_e64 s[18:19], 8, v2
	v_cndmask_b32_e32 v16, v152, v17, vcc
	s_and_b64 vcc, vcc, s[16:17]
	v_cmp_gt_i32_e64 s[20:21], 3, v2
	v_cndmask_b32_e32 v161, v151, v17, vcc
	s_and_b64 vcc, vcc, s[18:19]
	v_cmp_gt_i32_e64 s[22:23], 2, v2
	v_cndmask_b32_e32 v162, v150, v17, vcc
	s_and_b64 vcc, vcc, s[20:21]
	v_cmp_gt_i32_e64 s[24:25], 1, v2
	v_cndmask_b32_e32 v163, v149, v17, vcc
	s_and_b64 vcc, vcc, s[22:23]
	v_cmp_gt_i32_e64 s[26:27], 0, v2
	v_cndmask_b32_e32 v164, v148, v17, vcc
	s_and_b64 vcc, vcc, s[24:25]
	v_cndmask_b32_e32 v165, v147, v17, vcc
	s_and_b64 vcc, vcc, s[26:27]
	v_cndmask_b32_e32 v166, v146, v17, vcc
	v_cmp_eq_u32_e32 vcc, 58, v214
	v_cndmask_b32_e64 v2, v159, v17, s[28:29]
	s_nop 0
	v_cndmask_b32_e32 v9, v8, v153, vcc
	v_cndmask_b32_e32 v8, v16, v152, vcc
	v_cndmask_b32_e32 v16, v17, v160, vcc
	v_cndmask_b32_e32 v15, v2, v159, vcc
	v_cndmask_b32_e32 v14, v3, v158, vcc
	v_cndmask_b32_e32 v13, v4, v157, vcc
	v_cndmask_b32_e32 v12, v5, v156, vcc
	v_cndmask_b32_e32 v11, v6, v155, vcc
	v_cndmask_b32_e32 v10, v7, v154, vcc
	v_cndmask_b32_e32 v7, v161, v151, vcc
	v_cndmask_b32_e32 v6, v162, v150, vcc
	v_cndmask_b32_e32 v5, v163, v149, vcc
	v_cndmask_b32_e32 v4, v164, v148, vcc
	v_cndmask_b32_e32 v3, v165, v147, vcc
	v_cndmask_b32_e32 v2, v166, v146, vcc
	v_mov_b64_e32 v[160:161], v[16:17]
	v_mov_b64_e32 v[158:159], v[14:15]
	v_mov_b64_e32 v[156:157], v[12:13]
	v_mov_b64_e32 v[154:155], v[10:11]
	v_mov_b64_e32 v[152:153], v[8:9]
	v_mov_b64_e32 v[150:151], v[6:7]
	v_mov_b64_e32 v[148:149], v[4:5]
	v_mov_b64_e32 v[146:147], v[2:3]
